# prologue slimming: m0 save/restore pairs around the attention unit prologue's LDS-DMAs removed (m0 is dead outside DMA issue)
# speedup vs baseline: 1.0009x; 1.0009x over previous
.LBB0_144:
	s_or_b64 exec, exec, s[4:5]
	v_cndmask_b32_e64 v0, 0, 1, s[2:3]
	v_cmp_ne_u32_e32 vcc, 0, v0
	s_not_b64 s[2:3], vcc
	s_ff1_i32_b64 s2, s[2:3]
	v_readfirstlane_b32 s5, v32
	s_min_u32 s2, s2, 64
	s_ashr_i32 s13, s5, 6
	s_and_b32 s2, s2, 0x7e
	s_lshl_b32 s20, s13, 5
	s_min_u32 s40, s2, s6
	s_add_i32 s2, s14, s17
	s_ashr_i32 s3, s20, 31
	s_add_u32 s2, s20, s2
	s_addc_u32 s3, s3, 0
	s_lshl_b64 s[6:7], s[2:3], 11
	v_readlane_b32 s18, v252, 23
	v_readlane_b32 s19, v252, 24
	s_add_u32 s4, s18, s6
	s_addc_u32 s7, s19, s7
	s_add_u32 s6, s4, s12
	s_addc_u32 s7, s7, 0
	s_ashr_i32 s41, s40, 31
	s_lshl_b64 s[18:19], s[40:41], 16
	s_lshl_b32 s4, s15, 22
	s_add_u32 s18, s18, s4
	s_addc_u32 s19, s19, 0
	s_lshl_b64 s[18:19], s[18:19], 1
	s_add_u32 s4, s46, s18
	v_readlane_b32 s15, v252, 32
	s_addc_u32 s15, s15, s19
	s_add_u32 s52, s4, s12
	s_addc_u32 s53, s15, 0
	v_readlane_b32 s4, v252, 33
	s_add_u32 s4, s4, s18
	v_readlane_b32 s15, v252, 34
	v_mov_b32_e32 v0, s68
	v_and_b32_e32 v197, 63, v32
	s_addc_u32 s15, s15, s19
	ds_read_b32 v196, v0
	s_add_u32 s18, s4, s12
	v_lshlrev_b32_e32 v0, 11, v197
	v_mov_b32_e32 v1, v193
	s_addc_u32 s19, s15, 0
	v_lshl_add_u64 v[0:1], s[52:53], 0, v[0:1]
	s_lshl_b32 s52, s13, 3
	s_ashr_i32 s53, s52, 31
	v_lshl_add_u64 v[206:207], s[52:53], 1, v[0:1]
	s_lshl_b32 s4, s13, 4
	v_bfe_u32 v0, v32, 2, 4
	v_and_or_b32 v0, s4, 48, v0
	v_lshlrev_b32_e32 v0, 11, v0
	v_mov_b32_e32 v1, v193
	s_ashr_i32 s4, s5, 3
	v_lshl_add_u64 v[0:1], s[18:19], 0, v[0:1]
	s_and_b32 s18, s4, 0xffffffe0
	s_ashr_i32 s19, s18, 31
	s_lshl_b32 s4, s13, 10
	v_lshlrev_b32_e32 v210, 3, v32
	s_cmp_lg_u32 0, -1
	v_and_b32_e32 v213, 24, v210
	s_cselect_b32 s15, 0, 0
	v_bfe_u32 v212, v32, 5, 1
	v_lshl_add_u64 v[0:1], s[18:19], 1, v[0:1]
	v_lshlrev_b32_e32 v2, 1, v213
	v_mov_b32_e32 v3, v193
	s_add_i32 s18, s4, s15
	s_mov_b32 m0, s18
	s_nop 0
	global_load_lds_dwordx4 v[206:207], off
	s_mov_b64 s[22:23], 0x20000
	v_and_b32_e32 v211, 31, v32
	v_lshl_add_u64 v[208:209], v[0:1], 0, v[2:3]
	s_add_i32 s19, s18, 0x6000
	s_mov_b32 m0, s19
	s_nop 0
	global_load_lds_dwordx4 v[208:209], off
	v_lshl_add_u64 v[0:1], v[206:207], 0, s[22:23]
	v_lshlrev_b32_e32 v2, 4, v212
	s_add_i32 s15, s18, 0x2000
	s_mov_b32 m0, s15
	s_nop 0
	global_load_lds_dwordx4 v[0:1], off
	v_lshl_or_b32 v0, v211, 11, v2
	v_mov_b32_e32 v116, v14
	v_mov_b32_e32 v117, v15
	v_mov_b32_e32 v118, v16
	v_mov_b32_e32 v119, v17
	v_mov_b32_e32 v108, v18
	v_mov_b32_e32 v109, v19
	v_mov_b32_e32 v110, v20
	v_mov_b32_e32 v111, v21
	v_mov_b32_e32 v100, v22
	v_mov_b32_e32 v101, v23
	v_mov_b32_e32 v102, v24
	v_mov_b32_e32 v103, v25
	v_mov_b32_e32 v96, v26
	v_mov_b32_e32 v97, v27
	v_mov_b32_e32 v98, v28
	v_mov_b32_e32 v99, v29
	v_lshlrev_b32_e32 v0, 10, v212
	v_lshlrev_b32_e32 v1, 4, v211
	s_add_i32 s6, 0, 0x14800
	v_add3_u32 v220, 0, v0, v1
	v_lshl_add_u64 v[0:1], v[206:207], 0, s[88:89]
	v_add_u32_e32 v2, s6, v2
	s_add_i32 s6, s18, 0x4000
	s_mov_b32 s7, m0
	s_mov_b32 m0, s6
	s_nop 0
	global_load_lds_dwordx4 v[0:1], off
	s_mov_b32 m0, s7
	s_lshl_b32 s17, s40, 8
	s_waitcnt vmcnt(3) lgkmcnt(0)
	s_barrier
	v_add_u32_e32 v33, s17, v2
	ds_read_b128 v[20:23], v220
	ds_read_b128 v[0:3], v33
	ds_read_b128 v[4:7], v33 offset:32
	ds_read_b128 v[8:11], v33 offset:64
	ds_read_b128 v[12:15], v33 offset:96
	ds_read_b128 v[34:37], v220 offset:512
	ds_read_b128 v[16:19], v33 offset:128
	s_addk_i32 s14, 0x100
	s_lshr_b32 s26, s14, 6
	v_or_b32_e32 v219, s20, v211
	s_sub_i32 s20, s26, s40
	v_lshlrev_b32_e32 v218, 2, v212
	s_cmp_gt_i32 s20, 4
	s_waitcnt lgkmcnt(2)
	v_mfma_f32_32x32x16_bf16 v[0:15], v[20:23], v[116:119], v[0:15]
	ds_read_b128 v[20:23], v33 offset:160
	ds_read_b128 v[24:27], v33 offset:192
	ds_read_b128 v[28:31], v33 offset:224
	s_waitcnt lgkmcnt(0)
	v_mfma_f32_32x32x16_bf16 v[16:31], v[34:37], v[116:119], v[16:31]
	ds_read_b128 v[34:37], v220 offset:2048
	s_waitcnt lgkmcnt(0)
	v_mfma_f32_32x32x16_bf16 v[0:15], v[34:37], v[108:111], v[0:15]
	ds_read_b128 v[34:37], v220 offset:2560
	s_waitcnt lgkmcnt(0)
	v_mfma_f32_32x32x16_bf16 v[16:31], v[34:37], v[108:111], v[16:31]
	ds_read_b128 v[34:37], v220 offset:4096
	s_waitcnt lgkmcnt(0)
	v_mfma_f32_32x32x16_bf16 v[0:15], v[34:37], v[100:103], v[0:15]
	ds_read_b128 v[34:37], v220 offset:4608
	s_waitcnt lgkmcnt(0)
	v_mfma_f32_32x32x16_bf16 v[16:31], v[34:37], v[100:103], v[16:31]
	ds_read_b128 v[34:37], v220 offset:6144
	s_waitcnt lgkmcnt(0)
	v_mfma_f32_32x32x16_bf16 v[0:15], v[34:37], v[96:99], v[0:15]
	ds_read_b128 v[34:37], v220 offset:6656
	s_waitcnt lgkmcnt(0)
	v_mfma_f32_32x32x16_bf16 v[16:31], v[34:37], v[96:99], v[16:31]
	s_nop 15
	s_nop 7
	s_cbranch_scc1 .LBB0_146
	s_lshl_b32 s6, s20, 6
	v_subrev_u32_e32 v34, s6, v218
	v_add_u32_e32 v36, 0x120, v34
	v_add_u32_e32 v35, 0x100, v34
	v_cmp_le_i32_e32 vcc, v36, v219
	s_nop 5
	v_cndmask_b32_e32 v16, v238, v16, vcc
	v_cmp_lt_i32_e32 vcc, v35, v219
	s_nop 1
	v_cndmask_b32_e32 v1, v238, v1, vcc
	v_cmp_le_i32_e32 vcc, v35, v219
	v_add_u32_e32 v35, 0x121, v34
	s_nop 0
	v_cndmask_b32_e32 v0, v238, v0, vcc
	v_cmp_le_i32_e32 vcc, v35, v219
	v_add_u32_e32 v35, 0x102, v34
	s_nop 0
	v_cndmask_b32_e32 v17, v238, v17, vcc
	v_cmp_le_i32_e32 vcc, v35, v219
	v_add_u32_e32 v35, 0x122, v34
	s_nop 0
	v_cndmask_b32_e32 v2, v238, v2, vcc
	v_cmp_le_i32_e32 vcc, v35, v219
	v_add_u32_e32 v35, 0x103, v34
	s_nop 0
	v_cndmask_b32_e32 v18, v238, v18, vcc
	v_cmp_le_i32_e32 vcc, v35, v219
	v_add_u32_e32 v35, 0x123, v34
	s_nop 0
	v_cndmask_b32_e32 v3, v238, v3, vcc
	v_cmp_le_i32_e32 vcc, v35, v219
	v_add_u32_e32 v35, 0x108, v34
	s_nop 0
	v_cndmask_b32_e32 v19, v238, v19, vcc
	v_cmp_le_i32_e32 vcc, v35, v219
	v_add_u32_e32 v35, 0x128, v34
	s_nop 0
	v_cndmask_b32_e32 v4, v238, v4, vcc
	v_cmp_le_i32_e32 vcc, v35, v219
	v_add_u32_e32 v35, 0x109, v34
	s_nop 0
	v_cndmask_b32_e32 v20, v238, v20, vcc
	v_cmp_le_i32_e32 vcc, v35, v219
	v_add_u32_e32 v35, 0x129, v34
	s_nop 0
	v_cndmask_b32_e32 v5, v238, v5, vcc
	v_cmp_le_i32_e32 vcc, v35, v219
	v_add_u32_e32 v35, 0x10a, v34
	s_nop 0
	v_cndmask_b32_e32 v21, v238, v21, vcc
	v_cmp_le_i32_e32 vcc, v35, v219
	v_add_u32_e32 v35, 0x12a, v34
	s_nop 0
	v_cndmask_b32_e32 v6, v238, v6, vcc
	v_cmp_le_i32_e32 vcc, v35, v219
	v_add_u32_e32 v35, 0x10b, v34
	s_nop 0
	v_cndmask_b32_e32 v22, v238, v22, vcc
	v_cmp_le_i32_e32 vcc, v35, v219
	v_add_u32_e32 v35, 0x12b, v34
	s_nop 0
	v_cndmask_b32_e32 v7, v238, v7, vcc
	v_cmp_le_i32_e32 vcc, v35, v219
	v_add_u32_e32 v35, 0x110, v34
	s_nop 0
	v_cndmask_b32_e32 v23, v238, v23, vcc
	v_cmp_le_i32_e32 vcc, v35, v219
	v_add_u32_e32 v35, 0x130, v34
	s_nop 0
	v_cndmask_b32_e32 v8, v238, v8, vcc
	v_cmp_le_i32_e32 vcc, v35, v219
	v_add_u32_e32 v35, 0x111, v34
	s_nop 0
	v_cndmask_b32_e32 v24, v238, v24, vcc
	v_cmp_le_i32_e32 vcc, v35, v219
	v_add_u32_e32 v35, 0x131, v34
	s_nop 0
	v_cndmask_b32_e32 v9, v238, v9, vcc
	v_cmp_le_i32_e32 vcc, v35, v219
	v_add_u32_e32 v35, 0x112, v34
	s_nop 0
	v_cndmask_b32_e32 v25, v238, v25, vcc
	v_cmp_le_i32_e32 vcc, v35, v219
	v_add_u32_e32 v35, 0x132, v34
	s_nop 0
	v_cndmask_b32_e32 v10, v238, v10, vcc
	v_cmp_le_i32_e32 vcc, v35, v219
	v_add_u32_e32 v35, 0x113, v34
	s_nop 0
	v_cndmask_b32_e32 v26, v238, v26, vcc
	v_cmp_le_i32_e32 vcc, v35, v219
	v_add_u32_e32 v35, 0x133, v34
	s_nop 0
	v_cndmask_b32_e32 v11, v238, v11, vcc
	v_cmp_le_i32_e32 vcc, v35, v219
	v_add_u32_e32 v35, 0x118, v34
	s_nop 0
	v_cndmask_b32_e32 v27, v238, v27, vcc
	v_cmp_le_i32_e32 vcc, v35, v219
	v_add_u32_e32 v35, 0x138, v34
	s_nop 0
	v_cndmask_b32_e32 v12, v238, v12, vcc
	v_cmp_le_i32_e32 vcc, v35, v219
	v_add_u32_e32 v35, 0x119, v34
	s_nop 0
	v_cndmask_b32_e32 v28, v238, v28, vcc
	v_cmp_le_i32_e32 vcc, v35, v219
	v_add_u32_e32 v35, 0x139, v34
	s_nop 0
	v_cndmask_b32_e32 v13, v238, v13, vcc
	v_cmp_le_i32_e32 vcc, v35, v219
	v_add_u32_e32 v35, 0x11a, v34
	s_nop 0
	v_cndmask_b32_e32 v29, v238, v29, vcc
	v_cmp_le_i32_e32 vcc, v35, v219
	v_add_u32_e32 v35, 0x13a, v34
	s_nop 0
	v_cndmask_b32_e32 v14, v238, v14, vcc
	v_cmp_le_i32_e32 vcc, v35, v219
	v_add_u32_e32 v35, 0x11b, v34
	v_add_u32_e32 v34, 0x13b, v34
	v_cndmask_b32_e32 v30, v238, v30, vcc
	v_cmp_le_i32_e32 vcc, v35, v219
	s_nop 1
	v_cndmask_b32_e32 v15, v238, v15, vcc
	v_cmp_le_i32_e32 vcc, v34, v219
	s_nop 1
	v_cndmask_b32_e32 v31, v238, v31, vcc
